# combo2 + mixer-A/B epilogue dwordx4 stores + RMSNorm-scale table build reuses the previous unit's row sums when the address repeats
# speedup vs baseline: 1.0029x; 1.0029x over previous
.LBB0_41:
	v_readlane_b32 s8, v250, 11
	v_readlane_b32 s9, v250, 12
	s_load_dwordx2 s[22:23], s[8:9], 0x88
	v_mov_b32_e32 v2, v199
	s_movk_i32 s4, 0x100
	v_ashrrev_i32_e32 v3, 31, v2
	s_waitcnt lgkmcnt(0)
	s_add_u32 s6, s22, s66
	s_addc_u32 s7, s23, s67
	v_lshl_add_u64 v[0:1], v[2:3], 3, s[6:7]
	v_readlane_b32 s6, v250, 44
	v_cmp_gt_i32_e64 s[4:5], s4, v2
	v_add_u32_e32 v4, 0xfffffe00, v2
	v_lshl_add_u32 v5, v2, 2, s6
	s_mov_b32 s10, s55
	v_mov_b32_e32 v102, 0
	v_mov_b32_e32 v103, 0
	s_branch .LBB0_44

.LBB0_49:
	v_cmp_ne_u64_e32 vcc, v[2:3], v[102:103]
	s_cbranch_vccz .Lrst_reuse_0
	v_mov_b32_e32 v102, v2
	v_mov_b32_e32 v103, v3
	global_load_dwordx2 v[100:101], v[2:3], off
	s_waitcnt vmcnt(0)
.Lrst_reuse_0:
	v_mov_b32_e32 v8, v100
	v_mov_b32_e32 v9, v101
	v_add_u32_e32 v7, 0x200, v7
	v_lshl_add_u64 v[2:3], v[2:3], 0, s[62:63]
	s_waitcnt vmcnt(0)
	v_ffbh_u32_e32 v10, v9
	v_min_u32_e32 v10, 32, v10
	v_lshlrev_b64 v[8:9], v10, v[8:9]
	v_min_u32_e32 v8, 1, v8
	v_or_b32_e32 v8, v9, v8
	v_cvt_f32_u32_e32 v8, v8
	v_sub_u32_e32 v9, 32, v10
	v_ldexp_f32 v8, v8, v9
	v_fmamk_f32 v8, v8, 0x2e000000, v209
	v_cmp_gt_f32_e32 vcc, s49, v8
	v_mul_f32_e32 v9, 0x4b800000, v8
	s_nop 0
	v_cndmask_b32_e32 v8, v8, v9, vcc
	v_rsq_f32_e32 v8, v8
	s_nop 0
	v_mul_f32_e32 v9, 0x45800000, v8
	v_cndmask_b32_e32 v8, v8, v9, vcc
	v_cmp_lt_i32_e32 vcc, s50, v7
	ds_write_b32 v6, v8
	v_add_u32_e32 v6, 0x800, v6
	s_or_b64 s[12:13], vcc, s[12:13]
	s_andn2_b64 exec, exec, s[12:13]
	s_cbranch_execnz .LBB0_49
	s_branch .LBB0_42

; __device__ __forceinline__ unsigned pk_bf16(float lo, float hi) { return pg8::cvt_pk_bf16(lo, hi); }
; __device__ __forceinline__ float sq2(unsigned w) { const float a = bf_lo(w), b = bf_hi(w); return a * a + b * b; }
; template <int MODE> ...
;     ...
;     l += __shfl_xor(l, 32);
;     const float inv = 1.f / l;
;     bf16_t* og = obuf + (tokbase + qpos) * DM + ocol + 4 * h;
;     float qs = 0.f;
; #pragma unroll
;     for (int g = 0; g < 4; ++g) {
;         u32x2 a, c;
;         a.x = pk_bf16(o0[4 * g] * inv, o0[4 * g + 1] * inv); a.y = pk_bf16(o0[4 * g + 2] * inv, o0[4 * g + 3] * inv);
;         c.x = pk_bf16(o1[4 * g] * inv, o1[4 * g + 1] * inv); c.y = pk_bf16(o1[4 * g + 2] * inv, o1[4 * g + 3] * inv);
;         *(u32x2*)(og + 8 * g) = a; *(u32x2*)(og + 32 + 8 * g) = c;
;         qs += sq2(a.x) + sq2(a.y) + sq2(c.x) + sq2(c.y);
;     }
;     qs += __shfl_xor(qs, 32);
;     if (h == 0) atomicAdd(sg + tokbase + qpos, (unsigned long long)(qs * 16777216.f));
.LBB0_307:
	s_nop 1
	v_and_b32_e32 v34, 64, v221
	v_xor_b32_e32 v32, 32, v221
	v_add_u32_e32 v34, 64, v34
	v_cmp_lt_i32_e32 vcc, v32, v34
	v_lshlrev_b32_e32 v128, 3, v182
	s_nop 0
	v_cndmask_b32_e32 v32, v221, v32, vcc
	v_lshlrev_b32_e32 v158, 2, v32
	ds_bpermute_b32 v32, v158, v33
	s_waitcnt lgkmcnt(0)
	v_add_f32_e32 v32, v33, v32
	v_div_scale_f32 v33, s[4:5], v32, v32, 1.0
	v_rcp_f32_e32 v34, v33
	s_nop 0
	v_fma_f32 v35, -v33, v34, 1.0
	v_fmac_f32_e32 v34, v35, v34
	v_div_scale_f32 v35, vcc, 1.0, v32, 1.0
	v_mul_f32_e32 v36, v35, v34
	v_fma_f32 v37, -v33, v36, v35
	v_fmac_f32_e32 v36, v37, v34
	v_fma_f32 v33, -v33, v36, v35
	v_div_fmas_f32 v33, v33, v34, v36
	v_lshlrev_b64 v[34:35], 12, v[156:157]
	v_div_fixup_f32 v32, v33, v32, 1.0
	v_lshl_add_u64 v[34:35], s[88:89], 0, v[34:35]
	v_lshl_add_u64 v[34:35], s[90:91], 1, v[34:35]
	v_pk_mul_f32 v[0:1], v[0:1], v[32:33] op_sel_hi:[1,0]
	v_pk_mul_f32 v[2:3], v[2:3], v[32:33] op_sel_hi:[1,0]
	v_lshl_add_u64 v[34:35], v[34:35], 0, v[128:129]
	v_cvt_pk_bf16_f32 v0, v0, v1
	v_cvt_pk_bf16_f32 v1, v2, v3
	v_pk_mul_f32 v[2:3], v[16:17], v[32:33] op_sel_hi:[1,0]
	v_pk_mul_f32 v[16:17], v[18:19], v[32:33] op_sel_hi:[1,0]
	v_cvt_pk_bf16_f32 v2, v2, v3
	v_cvt_pk_bf16_f32 v3, v16, v17
	v_mov_b32_e32 v40, v0
	v_mov_b32_e32 v41, v1
	v_mov_b32_e32 v56, v34
	v_mov_b32_e32 v57, v35
	v_mov_b32_e32 v48, v2
	v_mov_b32_e32 v49, v3
	v_lshlrev_b32_e32 v16, 16, v0
	v_and_b32_e32 v0, 0xffff0000, v0
	v_mul_f32_e32 v0, v0, v0
	v_fmac_f32_e32 v0, v16, v16
	v_lshlrev_b32_e32 v16, 16, v1
	v_and_b32_e32 v1, 0xffff0000, v1
	v_mul_f32_e32 v1, v1, v1
	v_fmac_f32_e32 v1, v16, v16
	v_add_f32_e32 v0, v0, v1
	v_lshlrev_b32_e32 v1, 16, v2
	v_and_b32_e32 v2, 0xffff0000, v2
	v_mul_f32_e32 v2, v2, v2
	v_fmac_f32_e32 v2, v1, v1
	v_add_f32_e32 v0, v2, v0
	v_and_b32_e32 v2, 0xffff0000, v3
	v_lshlrev_b32_e32 v1, 16, v3
	v_mul_f32_e32 v2, v2, v2
	v_fmac_f32_e32 v2, v1, v1
	v_add_f32_e32 v16, v2, v0
	v_pk_mul_f32 v[0:1], v[4:5], v[32:33] op_sel_hi:[1,0]
	v_pk_mul_f32 v[2:3], v[6:7], v[32:33] op_sel_hi:[1,0]
	v_cvt_pk_bf16_f32 v0, v0, v1
	v_cvt_pk_bf16_f32 v1, v2, v3
	v_pk_mul_f32 v[2:3], v[20:21], v[32:33] op_sel_hi:[1,0]
	v_pk_mul_f32 v[4:5], v[22:23], v[32:33] op_sel_hi:[1,0]
	v_cvt_pk_bf16_f32 v2, v2, v3
	v_cvt_pk_bf16_f32 v3, v4, v5
	v_mov_b32_e32 v42, v0
	v_mov_b32_e32 v43, v1
	v_mov_b32_e32 v50, v2
	v_mov_b32_e32 v51, v3
	v_lshlrev_b32_e32 v4, 16, v0
	v_and_b32_e32 v0, 0xffff0000, v0
	v_mul_f32_e32 v0, v0, v0
	v_fmac_f32_e32 v0, v4, v4
	v_lshlrev_b32_e32 v4, 16, v1
	v_and_b32_e32 v1, 0xffff0000, v1
	v_mul_f32_e32 v1, v1, v1
	v_fmac_f32_e32 v1, v4, v4
	v_add_f32_e32 v0, v0, v1
	v_lshlrev_b32_e32 v1, 16, v2
	v_and_b32_e32 v2, 0xffff0000, v2
	v_mul_f32_e32 v2, v2, v2
	v_fmac_f32_e32 v2, v1, v1
	v_add_f32_e32 v0, v2, v0
	v_and_b32_e32 v2, 0xffff0000, v3
	v_lshlrev_b32_e32 v1, 16, v3
	v_mul_f32_e32 v2, v2, v2
	v_fmac_f32_e32 v2, v1, v1
	v_add_f32_e32 v0, v2, v0
	v_add_f32_e32 v6, v16, v0
	v_pk_mul_f32 v[0:1], v[8:9], v[32:33] op_sel_hi:[1,0]
	v_pk_mul_f32 v[2:3], v[10:11], v[32:33] op_sel_hi:[1,0]
	v_cvt_pk_bf16_f32 v0, v0, v1
	v_cvt_pk_bf16_f32 v1, v2, v3
	v_pk_mul_f32 v[2:3], v[24:25], v[32:33] op_sel_hi:[1,0]
	v_pk_mul_f32 v[4:5], v[26:27], v[32:33] op_sel_hi:[1,0]
	v_cvt_pk_bf16_f32 v2, v2, v3
	v_cvt_pk_bf16_f32 v3, v4, v5
	v_mov_b32_e32 v44, v0
	v_mov_b32_e32 v45, v1
	v_mov_b32_e32 v52, v2
	v_mov_b32_e32 v53, v3
	v_lshlrev_b32_e32 v4, 16, v0
	v_and_b32_e32 v0, 0xffff0000, v0
	v_mul_f32_e32 v0, v0, v0
	v_fmac_f32_e32 v0, v4, v4
	v_lshlrev_b32_e32 v4, 16, v1
	v_and_b32_e32 v1, 0xffff0000, v1
	v_mul_f32_e32 v1, v1, v1
	v_fmac_f32_e32 v1, v4, v4
	v_add_f32_e32 v0, v0, v1
	v_lshlrev_b32_e32 v1, 16, v2
	v_and_b32_e32 v2, 0xffff0000, v2
	v_mul_f32_e32 v2, v2, v2
	v_fmac_f32_e32 v2, v1, v1
	v_add_f32_e32 v0, v2, v0
	v_and_b32_e32 v2, 0xffff0000, v3
	v_lshlrev_b32_e32 v1, 16, v3
	v_mul_f32_e32 v2, v2, v2
	v_fmac_f32_e32 v2, v1, v1
	v_add_f32_e32 v0, v2, v0
	v_add_f32_e32 v6, v0, v6
	v_pk_mul_f32 v[0:1], v[12:13], v[32:33] op_sel_hi:[1,0]
	v_pk_mul_f32 v[2:3], v[14:15], v[32:33] op_sel_hi:[1,0]
	v_cvt_pk_bf16_f32 v0, v0, v1
	v_cvt_pk_bf16_f32 v1, v2, v3
	v_pk_mul_f32 v[2:3], v[28:29], v[32:33] op_sel_hi:[1,0]
	v_pk_mul_f32 v[4:5], v[30:31], v[32:33] op_sel_hi:[1,0]
	v_cvt_pk_bf16_f32 v2, v2, v3
	v_cvt_pk_bf16_f32 v3, v4, v5
	v_mov_b32_e32 v46, v0
	v_mov_b32_e32 v47, v1
	v_mov_b32_e32 v54, v2
	v_mov_b32_e32 v55, v3
	v_mbcnt_lo_u32_b32 v58, -1, 0
	v_mbcnt_hi_u32_b32 v58, -1, v58
	v_and_b32_e32 v58, 32, v58
	v_lshrrev_b32_e32 v58, 2, v58
	v_mov_b32_e32 v59, 0
	v_lshl_add_u64 v[56:57], v[56:57], 0, v[58:59]
	s_nop 1
	v_permlane32_swap_b32_e32 v40, v42
	v_permlane32_swap_b32_e32 v41, v43
	v_permlane32_swap_b32_e32 v44, v46
	v_permlane32_swap_b32_e32 v45, v47
	v_permlane32_swap_b32_e32 v48, v50
	v_permlane32_swap_b32_e32 v49, v51
	v_permlane32_swap_b32_e32 v52, v54
	v_permlane32_swap_b32_e32 v53, v55
	global_store_dwordx4 v[56:57], v[40:43], off
	global_store_dwordx4 v[56:57], v[44:47], off offset:32
	global_store_dwordx4 v[56:57], v[48:51], off offset:64
	global_store_dwordx4 v[56:57], v[52:55], off offset:96
	v_lshlrev_b32_e32 v4, 16, v0
	v_and_b32_e32 v0, 0xffff0000, v0
	v_mul_f32_e32 v0, v0, v0
	v_fmac_f32_e32 v0, v4, v4
	v_lshlrev_b32_e32 v4, 16, v1
	v_and_b32_e32 v1, 0xffff0000, v1
	v_mul_f32_e32 v1, v1, v1
	v_fmac_f32_e32 v1, v4, v4
	v_add_f32_e32 v0, v0, v1
	v_lshlrev_b32_e32 v1, 16, v2
	v_and_b32_e32 v2, 0xffff0000, v2
	v_mul_f32_e32 v2, v2, v2
	v_fmac_f32_e32 v2, v1, v1
	v_add_f32_e32 v0, v2, v0
	v_and_b32_e32 v2, 0xffff0000, v3
	v_lshlrev_b32_e32 v1, 16, v3
	v_mul_f32_e32 v2, v2, v2
	v_fmac_f32_e32 v2, v1, v1
	v_add_f32_e32 v0, v2, v0
	v_add_f32_e32 v0, v0, v6
	ds_bpermute_b32 v1, v158, v0
	s_and_saveexec_b64 s[20:21], s[6:7]
	s_cbranch_execz .LBB0_221
	s_waitcnt lgkmcnt(0)
	v_add_f32_e32 v0, v0, v1
	v_mul_f32_e32 v0, 0x4b800000, v0
	v_trunc_f32_e32 v0, v0
	v_mul_f32_e32 v1, 0x2f800000, v0
	v_floor_f32_e32 v1, v1
	v_fmac_f32_e32 v0, 0xcf800000, v1
	v_cvt_u32_f32_e32 v0, v0
	v_cvt_u32_f32_e32 v1, v1
	s_lshl_b32 s4, s54, 3
	s_add_u32 s4, s38, s4
	s_addc_u32 s5, s39, 0
	v_lshl_add_u64 v[2:3], v[154:155], 3, s[4:5]
	global_atomic_add_x2 v[2:3], v[0:1], off
	s_branch .LBB0_221

; __device__ __forceinline__ unsigned pk_bf16(float lo, float hi) { return pg8::cvt_pk_bf16(lo, hi); }
; __device__ __forceinline__ float sq2(unsigned w) { const float a = bf_lo(w), b = bf_hi(w); return a * a + b * b; }
; __device__ __forceinline__ void attn_b_unit(LAS unsigned char* lds, const bf16_t* proj, const bf16_t* vt, bf16_t* obuf, int b, int hk, int blk, const float* btab, unsigned long long* sg, bool build_lut, CP WP, int wlayer, int wbase) {
;     ...
;     l += __shfl_xor(l, 32);
;     const float inv = 1.f / l;
;     bf16_t* og = obuf + (tokbase + qpos) * DM + ocol + 4 * h;
;     float qs = 0.f;
; #pragma unroll
;     for (int g = 0; g < 4; ++g) {
;         u32x2 a, cc;
;         a.x = pk_bf16(o0[4 * g] * inv, o0[4 * g + 1] * inv); a.y = pk_bf16(o0[4 * g + 2] * inv, o0[4 * g + 3] * inv);
;         cc.x = pk_bf16(o1[4 * g] * inv, o1[4 * g + 1] * inv); cc.y = pk_bf16(o1[4 * g + 2] * inv, o1[4 * g + 3] * inv);
;         *(u32x2*)(og + 8 * g) = a; *(u32x2*)(og + 32 + 8 * g) = cc;
;         qs += sq2(a.x) + sq2(a.y) + sq2(cc.x) + sq2(cc.y);
;     }
;     qs += __shfl_xor(qs, 32);
;     if (h == 0) atomicAdd(sg + tokbase + qpos, (unsigned long long)(qs * 16777216.f));
.LBB0_391:
	ds_bpermute_b32 v32, v158, v156
	s_waitcnt lgkmcnt(0)
	v_add_f32_e32 v32, v156, v32
	v_div_scale_f32 v33, s[4:5], v32, v32, 1.0
	v_rcp_f32_e32 v34, v33
	s_lshl_b32 s4, s53, 1
	s_mov_b32 s5, s55
	v_fma_f32 v35, -v33, v34, 1.0
	v_fmac_f32_e32 v34, v35, v34
	v_div_scale_f32 v35, vcc, 1.0, v32, 1.0
	v_mul_f32_e32 v36, v35, v34
	v_fma_f32 v37, -v33, v36, v35
	v_fmac_f32_e32 v36, v37, v34
	v_fma_f32 v33, -v33, v36, v35
	v_div_fmas_f32 v33, v33, v34, v36
	v_lshlrev_b64 v[34:35], 12, v[140:141]
	v_div_fixup_f32 v32, v33, v32, 1.0
	v_lshl_add_u64 v[34:35], s[88:89], 0, v[34:35]
	v_lshl_add_u64 v[34:35], v[34:35], 0, s[4:5]
	v_pk_mul_f32 v[0:1], v[0:1], v[32:33] op_sel_hi:[1,0]
	v_pk_mul_f32 v[2:3], v[2:3], v[32:33] op_sel_hi:[1,0]
	v_lshl_add_u64 v[34:35], v[34:35], 0, v[128:129]
	v_cvt_pk_bf16_f32 v0, v0, v1
	v_cvt_pk_bf16_f32 v1, v2, v3
	v_pk_mul_f32 v[2:3], v[16:17], v[32:33] op_sel_hi:[1,0]
	v_pk_mul_f32 v[16:17], v[18:19], v[32:33] op_sel_hi:[1,0]
	v_cvt_pk_bf16_f32 v2, v2, v3
	v_cvt_pk_bf16_f32 v3, v16, v17
	v_mov_b32_e32 v40, v0
	v_mov_b32_e32 v41, v1
	v_mov_b32_e32 v56, v34
	v_mov_b32_e32 v57, v35
	v_mov_b32_e32 v48, v2
	v_mov_b32_e32 v49, v3
	v_lshlrev_b32_e32 v16, 16, v0
	v_and_b32_e32 v0, 0xffff0000, v0
	v_mul_f32_e32 v0, v0, v0
	v_fmac_f32_e32 v0, v16, v16
	v_lshlrev_b32_e32 v16, 16, v1
	v_and_b32_e32 v1, 0xffff0000, v1
	v_mul_f32_e32 v1, v1, v1
	v_fmac_f32_e32 v1, v16, v16
	v_add_f32_e32 v0, v0, v1
	v_lshlrev_b32_e32 v1, 16, v2
	v_and_b32_e32 v2, 0xffff0000, v2
	v_mul_f32_e32 v2, v2, v2
	v_fmac_f32_e32 v2, v1, v1
	v_add_f32_e32 v0, v2, v0
	v_and_b32_e32 v2, 0xffff0000, v3
	v_lshlrev_b32_e32 v1, 16, v3
	v_mul_f32_e32 v2, v2, v2
	v_fmac_f32_e32 v2, v1, v1
	v_add_f32_e32 v16, v2, v0
	v_pk_mul_f32 v[0:1], v[4:5], v[32:33] op_sel_hi:[1,0]
	v_pk_mul_f32 v[2:3], v[6:7], v[32:33] op_sel_hi:[1,0]
	v_cvt_pk_bf16_f32 v0, v0, v1
	v_cvt_pk_bf16_f32 v1, v2, v3
	v_pk_mul_f32 v[2:3], v[20:21], v[32:33] op_sel_hi:[1,0]
	v_pk_mul_f32 v[4:5], v[22:23], v[32:33] op_sel_hi:[1,0]
	v_cvt_pk_bf16_f32 v2, v2, v3
	v_cvt_pk_bf16_f32 v3, v4, v5
	v_mov_b32_e32 v42, v0
	v_mov_b32_e32 v43, v1
	v_mov_b32_e32 v50, v2
	v_mov_b32_e32 v51, v3
	v_lshlrev_b32_e32 v4, 16, v0
	v_and_b32_e32 v0, 0xffff0000, v0
	v_mul_f32_e32 v0, v0, v0
	v_fmac_f32_e32 v0, v4, v4
	v_lshlrev_b32_e32 v4, 16, v1
	v_and_b32_e32 v1, 0xffff0000, v1
	v_mul_f32_e32 v1, v1, v1
	v_fmac_f32_e32 v1, v4, v4
	v_add_f32_e32 v0, v0, v1
	v_lshlrev_b32_e32 v1, 16, v2
	v_and_b32_e32 v2, 0xffff0000, v2
	v_mul_f32_e32 v2, v2, v2
	v_fmac_f32_e32 v2, v1, v1
	v_add_f32_e32 v0, v2, v0
	v_and_b32_e32 v2, 0xffff0000, v3
	v_lshlrev_b32_e32 v1, 16, v3
	v_mul_f32_e32 v2, v2, v2
	v_fmac_f32_e32 v2, v1, v1
	v_add_f32_e32 v0, v2, v0
	v_add_f32_e32 v6, v16, v0
	v_pk_mul_f32 v[0:1], v[8:9], v[32:33] op_sel_hi:[1,0]
	v_pk_mul_f32 v[2:3], v[10:11], v[32:33] op_sel_hi:[1,0]
	v_cvt_pk_bf16_f32 v0, v0, v1
	v_cvt_pk_bf16_f32 v1, v2, v3
	v_pk_mul_f32 v[2:3], v[24:25], v[32:33] op_sel_hi:[1,0]
	v_pk_mul_f32 v[4:5], v[26:27], v[32:33] op_sel_hi:[1,0]
	v_cvt_pk_bf16_f32 v2, v2, v3
	v_cvt_pk_bf16_f32 v3, v4, v5
	v_mov_b32_e32 v44, v0
	v_mov_b32_e32 v45, v1
	v_mov_b32_e32 v52, v2
	v_mov_b32_e32 v53, v3
	v_lshlrev_b32_e32 v4, 16, v0
	v_and_b32_e32 v0, 0xffff0000, v0
	v_mul_f32_e32 v0, v0, v0
	v_fmac_f32_e32 v0, v4, v4
	v_lshlrev_b32_e32 v4, 16, v1
	v_and_b32_e32 v1, 0xffff0000, v1
	v_mul_f32_e32 v1, v1, v1
	v_fmac_f32_e32 v1, v4, v4
	v_add_f32_e32 v0, v0, v1
	v_lshlrev_b32_e32 v1, 16, v2
	v_and_b32_e32 v2, 0xffff0000, v2
	v_mul_f32_e32 v2, v2, v2
	v_fmac_f32_e32 v2, v1, v1
	v_add_f32_e32 v0, v2, v0
	v_and_b32_e32 v2, 0xffff0000, v3
	v_lshlrev_b32_e32 v1, 16, v3
	v_mul_f32_e32 v2, v2, v2
	v_fmac_f32_e32 v2, v1, v1
	v_add_f32_e32 v0, v2, v0
	v_add_f32_e32 v6, v0, v6
	v_pk_mul_f32 v[0:1], v[12:13], v[32:33] op_sel_hi:[1,0]
	v_pk_mul_f32 v[2:3], v[14:15], v[32:33] op_sel_hi:[1,0]
	v_cvt_pk_bf16_f32 v0, v0, v1
	v_cvt_pk_bf16_f32 v1, v2, v3
	v_pk_mul_f32 v[2:3], v[28:29], v[32:33] op_sel_hi:[1,0]
	v_pk_mul_f32 v[4:5], v[30:31], v[32:33] op_sel_hi:[1,0]
	v_cvt_pk_bf16_f32 v2, v2, v3
	v_cvt_pk_bf16_f32 v3, v4, v5
	v_mov_b32_e32 v46, v0
	v_mov_b32_e32 v47, v1
	v_mov_b32_e32 v54, v2
	v_mov_b32_e32 v55, v3
	v_mbcnt_lo_u32_b32 v58, -1, 0
	v_mbcnt_hi_u32_b32 v58, -1, v58
	v_and_b32_e32 v58, 32, v58
	v_lshrrev_b32_e32 v58, 2, v58
	v_mov_b32_e32 v59, 0
	v_lshl_add_u64 v[56:57], v[56:57], 0, v[58:59]
	s_nop 1
	v_permlane32_swap_b32_e32 v40, v42
	v_permlane32_swap_b32_e32 v41, v43
	v_permlane32_swap_b32_e32 v44, v46
	v_permlane32_swap_b32_e32 v45, v47
	v_permlane32_swap_b32_e32 v48, v50
	v_permlane32_swap_b32_e32 v49, v51
	v_permlane32_swap_b32_e32 v52, v54
	v_permlane32_swap_b32_e32 v53, v55
	global_store_dwordx4 v[56:57], v[40:43], off offset:1024
	global_store_dwordx4 v[56:57], v[44:47], off offset:1056
	global_store_dwordx4 v[56:57], v[48:51], off offset:1088
	global_store_dwordx4 v[56:57], v[52:55], off offset:1120
	v_lshlrev_b32_e32 v4, 16, v0
	v_and_b32_e32 v0, 0xffff0000, v0
	v_mul_f32_e32 v0, v0, v0
	v_fmac_f32_e32 v0, v4, v4
	v_lshlrev_b32_e32 v4, 16, v1
	v_and_b32_e32 v1, 0xffff0000, v1
	v_mul_f32_e32 v1, v1, v1
	v_fmac_f32_e32 v1, v4, v4
	v_add_f32_e32 v0, v0, v1
	v_lshlrev_b32_e32 v1, 16, v2
	v_and_b32_e32 v2, 0xffff0000, v2
	v_mul_f32_e32 v2, v2, v2
	v_fmac_f32_e32 v2, v1, v1
	v_add_f32_e32 v0, v2, v0
	v_and_b32_e32 v2, 0xffff0000, v3
	v_lshlrev_b32_e32 v1, 16, v3
	v_mul_f32_e32 v2, v2, v2
	v_fmac_f32_e32 v2, v1, v1
	v_add_f32_e32 v0, v2, v0
	v_add_f32_e32 v0, v0, v6
	ds_bpermute_b32 v1, v158, v0
	v_cmp_gt_u32_e32 vcc, 32, v154
	s_and_saveexec_b64 s[6:7], vcc
	s_cbranch_execz .LBB0_312
	s_waitcnt lgkmcnt(0)
	v_add_f32_e32 v0, v0, v1
	v_mul_f32_e32 v0, 0x4b800000, v0
	v_trunc_f32_e32 v0, v0
	v_mul_f32_e32 v1, 0x2f800000, v0
	v_floor_f32_e32 v1, v1
	v_fmac_f32_e32 v0, 0xcf800000, v1
	v_cvt_u32_f32_e32 v0, v0
	v_cvt_u32_f32_e32 v1, v1
	s_lshl_b32 s4, s54, 3
	s_add_u32 s4, s24, s4
	s_addc_u32 s5, s36, 0
	v_lshl_add_u64 v[2:3], v[138:139], 3, s[4:5]
	global_atomic_add_x2 v[2:3], v[0:1], off
	s_branch .LBB0_312

; __global__ void __launch_bounds__(512, 2) hymba_fwd(Params Parg) {
;     ...
;             BUILD_RSTAB(S, (const unsigned long long*)(ws + WS_SS) + (size_t)(2 * layer + 1) * MTOK);
.LBB0_556:
	s_or_b64 exec, exec, s[6:7]
	v_readlane_b32 s4, v250, 11
	v_readlane_b32 s5, v250, 12
	s_waitcnt lgkmcnt(0)
	s_barrier
	s_load_dwordx2 s[14:15], s[4:5], 0x88
	v_mov_b32_e32 v2, v199
	s_movk_i32 s4, 0x100
	s_nop 0
	v_cmp_gt_i32_e64 s[6:7], s4, v2
	s_waitcnt lgkmcnt(0)
	s_add_u32 s4, s14, s60
	v_ashrrev_i32_e32 v3, 31, v2
	s_addc_u32 s5, s15, s61
	v_lshl_add_u64 v[0:1], v[2:3], 3, s[4:5]
	v_readlane_b32 s4, v250, 44
	v_add_u32_e32 v4, 0xfffffe00, v2
	s_nop 0
	v_lshl_add_u32 v5, v2, 2, s4
	s_mov_b32 s4, 0
	v_mov_b32_e32 v102, 0
	v_mov_b32_e32 v103, 0
	s_branch .LBB0_559
